# removed the s_setprio 0/1 pair that sat between the two MFMA blocks of each K-loop segment (proj, gate-up)
# speedup vs baseline: 1.0205x; 1.0039x over previous
.Lpj_skip1:
	s_waitcnt lgkmcnt(0)
	s_barrier
	s_setprio 1
	s_waitcnt lgkmcnt(0)
	v_mfma_f32_16x16x32_bf16 v[128:131], v[154:157], v[196:199], v[128:131]
	v_mfma_f32_16x16x32_bf16 v[124:127], v[172:175], v[196:199], v[124:127]
	v_mfma_f32_16x16x32_bf16 v[116:119], v[154:157], v[204:207], v[116:119]
	v_mfma_f32_16x16x32_bf16 v[108:111], v[172:175], v[204:207], v[108:111]
	v_mfma_f32_16x16x32_bf16 v[100:103], v[154:157], v[212:215], v[100:103]
	v_mfma_f32_16x16x32_bf16 v[92:95], v[172:175], v[212:215], v[92:95]
	v_mfma_f32_16x16x32_bf16 v[84:87], v[154:157], v[220:223], v[84:87]
	v_mfma_f32_16x16x32_bf16 v[76:79], v[172:175], v[220:223], v[76:79]
	v_mfma_f32_16x16x32_bf16 v[128:131], v[168:171], v[200:203], v[128:131]
	v_mfma_f32_16x16x32_bf16 v[124:127], v[176:179], v[200:203], v[124:127]
	v_mfma_f32_16x16x32_bf16 v[116:119], v[168:171], v[208:211], v[116:119]
	v_mfma_f32_16x16x32_bf16 v[108:111], v[176:179], v[208:211], v[108:111]
	v_mfma_f32_16x16x32_bf16 v[100:103], v[168:171], v[216:219], v[100:103]
	v_mfma_f32_16x16x32_bf16 v[92:95], v[176:179], v[216:219], v[92:95]
	v_mfma_f32_16x16x32_bf16 v[84:87], v[168:171], v[224:227], v[84:87]
	v_mfma_f32_16x16x32_bf16 v[76:79], v[176:179], v[224:227], v[76:79]
	v_mfma_f32_16x16x32_bf16 v[120:123], v[180:183], v[196:199], v[120:123]
	v_mfma_f32_16x16x32_bf16 v[112:115], v[188:191], v[196:199], v[112:115]
	v_mfma_f32_16x16x32_bf16 v[104:107], v[180:183], v[204:207], v[104:107]
	v_mfma_f32_16x16x32_bf16 v[96:99], v[188:191], v[204:207], v[96:99]
	v_mfma_f32_16x16x32_bf16 v[88:91], v[180:183], v[212:215], v[88:91]
	v_mfma_f32_16x16x32_bf16 v[80:83], v[188:191], v[212:215], v[80:83]
	v_mfma_f32_16x16x32_bf16 v[72:75], v[180:183], v[220:223], v[72:75]
	v_mfma_f32_16x16x32_bf16 v[68:71], v[188:191], v[220:223], v[68:71]
	v_mfma_f32_16x16x32_bf16 v[120:123], v[184:187], v[200:203], v[120:123]
	v_mfma_f32_16x16x32_bf16 v[112:115], v[192:195], v[200:203], v[112:115]
	v_mfma_f32_16x16x32_bf16 v[104:107], v[184:187], v[208:211], v[104:107]
	v_mfma_f32_16x16x32_bf16 v[96:99], v[192:195], v[208:211], v[96:99]
	v_mfma_f32_16x16x32_bf16 v[88:91], v[184:187], v[216:219], v[88:91]
	v_mfma_f32_16x16x32_bf16 v[80:83], v[192:195], v[216:219], v[80:83]
	v_mfma_f32_16x16x32_bf16 v[72:75], v[184:187], v[224:227], v[72:75]
	v_mfma_f32_16x16x32_bf16 v[68:71], v[192:195], v[224:227], v[68:71]
	s_setprio 0
	s_barrier
	s_add_i32 s43, s50, s10
	s_mov_b32 m0, s43
	ds_read_b128 v[196:199], v167 offset:16384
	ds_read_b128 v[200:203], v167 offset:17408
	ds_read_b128 v[204:207], v167 offset:18432
	ds_read_b128 v[208:211], v167 offset:19456
	ds_read_b128 v[212:215], v167 offset:20480
	ds_read_b128 v[216:219], v167 offset:21504
	ds_read_b128 v[220:223], v167 offset:22528
	ds_read_b128 v[224:227], v167 offset:23552
	global_load_lds_dwordx4 v2, s[46:47]
	s_add_i32 m0, s43, 0x2000
	s_add_u32 s50, s46, 0x80000
	s_addc_u32 s51, s47, 0
	s_add_i32 s33, s33, s10
	global_load_lds_dwordx4 v0, s[46:47]
	s_mov_b32 m0, s33
	s_nop 0
	global_load_lds_dwordx4 v2, s[50:51]
	s_add_i32 m0, s33, 0x2000
	s_nop 0
	global_load_lds_dwordx4 v0, s[50:51]
	s_mov_b32 m0, s12
	s_nop 0
	global_load_lds_dwordx4 v134, s[48:49]
	s_mov_b32 m0, s13
	s_nop 0
	global_load_lds_dwordx4 v132, s[48:49]
	s_cmp_lg_u32 s32, 0
	s_cbranch_scc1 .Lpj_skip2
	s_waitcnt vmcnt(8)
.Lpj_skip2:
	s_mov_b32 s32, 0
	s_waitcnt lgkmcnt(0)
	s_barrier
	s_setprio 1
	s_waitcnt lgkmcnt(0)
	v_mfma_f32_16x16x32_bf16 v[64:67], v[154:157], v[196:199], v[64:67]
	v_mfma_f32_16x16x32_bf16 v[60:63], v[172:175], v[196:199], v[60:63]
	v_mfma_f32_16x16x32_bf16 v[52:55], v[154:157], v[204:207], v[52:55]
	v_mfma_f32_16x16x32_bf16 v[44:47], v[172:175], v[204:207], v[44:47]
	v_mfma_f32_16x16x32_bf16 v[36:39], v[154:157], v[212:215], v[36:39]
	v_mfma_f32_16x16x32_bf16 v[28:31], v[172:175], v[212:215], v[28:31]
	v_mfma_f32_16x16x32_bf16 v[20:23], v[154:157], v[220:223], v[20:23]
	v_mfma_f32_16x16x32_bf16 v[12:15], v[172:175], v[220:223], v[12:15]
	v_mfma_f32_16x16x32_bf16 v[64:67], v[168:171], v[200:203], v[64:67]
	v_mfma_f32_16x16x32_bf16 v[60:63], v[176:179], v[200:203], v[60:63]
	v_mfma_f32_16x16x32_bf16 v[52:55], v[168:171], v[208:211], v[52:55]
	v_mfma_f32_16x16x32_bf16 v[44:47], v[176:179], v[208:211], v[44:47]
	v_mfma_f32_16x16x32_bf16 v[36:39], v[168:171], v[216:219], v[36:39]
	v_mfma_f32_16x16x32_bf16 v[28:31], v[176:179], v[216:219], v[28:31]
	v_mfma_f32_16x16x32_bf16 v[20:23], v[168:171], v[224:227], v[20:23]
	v_mfma_f32_16x16x32_bf16 v[12:15], v[176:179], v[224:227], v[12:15]
	v_mfma_f32_16x16x32_bf16 v[56:59], v[180:183], v[196:199], v[56:59]
	v_mfma_f32_16x16x32_bf16 v[48:51], v[188:191], v[196:199], v[48:51]
	v_mfma_f32_16x16x32_bf16 v[40:43], v[180:183], v[204:207], v[40:43]
	v_mfma_f32_16x16x32_bf16 v[32:35], v[188:191], v[204:207], v[32:35]
	v_mfma_f32_16x16x32_bf16 v[24:27], v[180:183], v[212:215], v[24:27]
	v_mfma_f32_16x16x32_bf16 v[16:19], v[188:191], v[212:215], v[16:19]
	v_mfma_f32_16x16x32_bf16 v[8:11], v[180:183], v[220:223], v[8:11]
	v_mfma_f32_16x16x32_bf16 v[4:7], v[188:191], v[220:223], v[4:7]
	v_mfma_f32_16x16x32_bf16 v[56:59], v[184:187], v[200:203], v[56:59]
	v_mfma_f32_16x16x32_bf16 v[48:51], v[192:195], v[200:203], v[48:51]
	v_mfma_f32_16x16x32_bf16 v[40:43], v[184:187], v[208:211], v[40:43]
	v_mfma_f32_16x16x32_bf16 v[32:35], v[192:195], v[208:211], v[32:35]
	v_mfma_f32_16x16x32_bf16 v[24:27], v[184:187], v[216:219], v[24:27]
	v_mfma_f32_16x16x32_bf16 v[16:19], v[192:195], v[216:219], v[16:19]
	v_mfma_f32_16x16x32_bf16 v[8:11], v[184:187], v[224:227], v[8:11]
	v_mfma_f32_16x16x32_bf16 v[4:7], v[192:195], v[224:227], v[4:7]
	s_setprio 0
	s_barrier
	s_add_i32 s33, 0, 0x18000
	v_add_u32_e32 v144, s33, v149
	s_add_i32 s43, 0, 0x1c000
	ds_read_b128 v[154:157], v144
	ds_read_b128 v[168:171], v144 offset:1024
	ds_read_b128 v[172:175], v144 offset:2048
	ds_read_b128 v[176:179], v144 offset:3072
	v_add_u32_e32 v144, s43, v149
	ds_read_b128 v[180:183], v144
	ds_read_b128 v[184:187], v144 offset:1024
	ds_read_b128 v[188:191], v144 offset:2048
	ds_read_b128 v[192:195], v144 offset:3072
	s_add_u32 s48, s48, 0x80000
	s_addc_u32 s49, s49, 0
	s_mov_b32 m0, s14
	ds_read_b128 v[196:199], v167 offset:32768
	ds_read_b128 v[200:203], v167 offset:33792
	ds_read_b128 v[204:207], v167 offset:34816
	ds_read_b128 v[208:211], v167 offset:35840
	ds_read_b128 v[212:215], v167 offset:36864
	ds_read_b128 v[216:219], v167 offset:37888
	ds_read_b128 v[220:223], v167 offset:38912
	ds_read_b128 v[224:227], v167 offset:39936
	global_load_lds_dwordx4 v134, s[48:49]
	s_mov_b32 m0, s15
	s_nop 0
	global_load_lds_dwordx4 v132, s[48:49]
	s_waitcnt vmcnt(8)
	s_waitcnt lgkmcnt(0)
	s_barrier
	s_setprio 1
	s_waitcnt lgkmcnt(0)
	v_mfma_f32_16x16x32_bf16 v[128:131], v[154:157], v[196:199], v[128:131]
	v_mfma_f32_16x16x32_bf16 v[124:127], v[172:175], v[196:199], v[124:127]
	v_mfma_f32_16x16x32_bf16 v[116:119], v[154:157], v[204:207], v[116:119]
	v_mfma_f32_16x16x32_bf16 v[108:111], v[172:175], v[204:207], v[108:111]
	v_mfma_f32_16x16x32_bf16 v[100:103], v[154:157], v[212:215], v[100:103]
	v_mfma_f32_16x16x32_bf16 v[92:95], v[172:175], v[212:215], v[92:95]
	v_mfma_f32_16x16x32_bf16 v[84:87], v[154:157], v[220:223], v[84:87]
	v_mfma_f32_16x16x32_bf16 v[76:79], v[172:175], v[220:223], v[76:79]
	v_mfma_f32_16x16x32_bf16 v[128:131], v[168:171], v[200:203], v[128:131]
	v_mfma_f32_16x16x32_bf16 v[124:127], v[176:179], v[200:203], v[124:127]
	v_mfma_f32_16x16x32_bf16 v[116:119], v[168:171], v[208:211], v[116:119]
	v_mfma_f32_16x16x32_bf16 v[108:111], v[176:179], v[208:211], v[108:111]
	v_mfma_f32_16x16x32_bf16 v[100:103], v[168:171], v[216:219], v[100:103]
	v_mfma_f32_16x16x32_bf16 v[92:95], v[176:179], v[216:219], v[92:95]
	v_mfma_f32_16x16x32_bf16 v[84:87], v[168:171], v[224:227], v[84:87]
	v_mfma_f32_16x16x32_bf16 v[76:79], v[176:179], v[224:227], v[76:79]
	v_mfma_f32_16x16x32_bf16 v[120:123], v[180:183], v[196:199], v[120:123]
	v_mfma_f32_16x16x32_bf16 v[112:115], v[188:191], v[196:199], v[112:115]
	v_mfma_f32_16x16x32_bf16 v[104:107], v[180:183], v[204:207], v[104:107]
	v_mfma_f32_16x16x32_bf16 v[96:99], v[188:191], v[204:207], v[96:99]
	v_mfma_f32_16x16x32_bf16 v[88:91], v[180:183], v[212:215], v[88:91]
	v_mfma_f32_16x16x32_bf16 v[80:83], v[188:191], v[212:215], v[80:83]
	v_mfma_f32_16x16x32_bf16 v[72:75], v[180:183], v[220:223], v[72:75]
	v_mfma_f32_16x16x32_bf16 v[68:71], v[188:191], v[220:223], v[68:71]
	v_mfma_f32_16x16x32_bf16 v[120:123], v[184:187], v[200:203], v[120:123]
	v_mfma_f32_16x16x32_bf16 v[112:115], v[192:195], v[200:203], v[112:115]
	v_mfma_f32_16x16x32_bf16 v[104:107], v[184:187], v[208:211], v[104:107]
	v_mfma_f32_16x16x32_bf16 v[96:99], v[192:195], v[208:211], v[96:99]
	v_mfma_f32_16x16x32_bf16 v[88:91], v[184:187], v[216:219], v[88:91]
	v_mfma_f32_16x16x32_bf16 v[80:83], v[192:195], v[216:219], v[80:83]
	v_mfma_f32_16x16x32_bf16 v[72:75], v[184:187], v[224:227], v[72:75]
	v_mfma_f32_16x16x32_bf16 v[68:71], v[192:195], v[224:227], v[68:71]
	s_setprio 0
	s_barrier
	s_add_i32 s33, s33, s10
	s_mov_b32 m0, s33
	ds_read_b128 v[196:199], v167 offset:49152
	ds_read_b128 v[200:203], v167 offset:50176
	ds_read_b128 v[204:207], v167 offset:51200
	ds_read_b128 v[208:211], v167 offset:52224
	ds_read_b128 v[212:215], v167 offset:53248
	ds_read_b128 v[216:219], v167 offset:54272
	ds_read_b128 v[220:223], v167 offset:55296
	ds_read_b128 v[224:227], v167 offset:56320
	s_add_u32 s100, s46, 0x80
	s_addc_u32 s101, s47, 0
	global_load_lds_dwordx4 v2, s[100:101]
	s_add_i32 m0, s33, 0x2000
	s_add_u32 s46, s46, 0x80080
	s_addc_u32 s47, s47, 0
	s_add_i32 s33, s43, s10
	s_add_u32 s100, s46, 0xfff80000
	s_addc_u32 s101, s47, -1
	global_load_lds_dwordx4 v0, s[100:101]
	s_mov_b32 m0, s33
	s_nop 0
	global_load_lds_dwordx4 v2, s[46:47]
	s_add_i32 m0, s33, 0x2000
	s_nop 0
	global_load_lds_dwordx4 v0, s[46:47]
	s_mov_b32 m0, s16
	s_nop 0
	s_add_u32 s100, s48, 0xfff80080
	s_addc_u32 s101, s49, -1
	global_load_lds_dwordx4 v134, s[100:101]
	s_mov_b32 m0, s17
	s_nop 0
	s_add_u32 s100, s48, 0xfff80080
	s_addc_u32 s101, s49, -1
	global_load_lds_dwordx4 v132, s[100:101]
	s_waitcnt vmcnt(8)
	s_waitcnt lgkmcnt(0)
	s_barrier
	s_setprio 1
	s_waitcnt lgkmcnt(0)
	v_mfma_f32_16x16x32_bf16 v[64:67], v[154:157], v[196:199], v[64:67]
	v_mfma_f32_16x16x32_bf16 v[60:63], v[172:175], v[196:199], v[60:63]
	v_mfma_f32_16x16x32_bf16 v[52:55], v[154:157], v[204:207], v[52:55]
	v_mfma_f32_16x16x32_bf16 v[44:47], v[172:175], v[204:207], v[44:47]
	v_mfma_f32_16x16x32_bf16 v[36:39], v[154:157], v[212:215], v[36:39]
	v_mfma_f32_16x16x32_bf16 v[28:31], v[172:175], v[212:215], v[28:31]
	v_mfma_f32_16x16x32_bf16 v[20:23], v[154:157], v[220:223], v[20:23]
	v_mfma_f32_16x16x32_bf16 v[12:15], v[172:175], v[220:223], v[12:15]
	v_mfma_f32_16x16x32_bf16 v[64:67], v[168:171], v[200:203], v[64:67]
	v_mfma_f32_16x16x32_bf16 v[60:63], v[176:179], v[200:203], v[60:63]
	v_mfma_f32_16x16x32_bf16 v[52:55], v[168:171], v[208:211], v[52:55]
	v_mfma_f32_16x16x32_bf16 v[44:47], v[176:179], v[208:211], v[44:47]
	v_mfma_f32_16x16x32_bf16 v[36:39], v[168:171], v[216:219], v[36:39]
	v_mfma_f32_16x16x32_bf16 v[28:31], v[176:179], v[216:219], v[28:31]
	v_mfma_f32_16x16x32_bf16 v[20:23], v[168:171], v[224:227], v[20:23]
	v_mfma_f32_16x16x32_bf16 v[12:15], v[176:179], v[224:227], v[12:15]
	v_mfma_f32_16x16x32_bf16 v[56:59], v[180:183], v[196:199], v[56:59]
	v_mfma_f32_16x16x32_bf16 v[48:51], v[188:191], v[196:199], v[48:51]
	v_mfma_f32_16x16x32_bf16 v[40:43], v[180:183], v[204:207], v[40:43]
	v_mfma_f32_16x16x32_bf16 v[32:35], v[188:191], v[204:207], v[32:35]
	v_mfma_f32_16x16x32_bf16 v[24:27], v[180:183], v[212:215], v[24:27]
	v_mfma_f32_16x16x32_bf16 v[16:19], v[188:191], v[212:215], v[16:19]
	v_mfma_f32_16x16x32_bf16 v[8:11], v[180:183], v[220:223], v[8:11]
	v_mfma_f32_16x16x32_bf16 v[4:7], v[188:191], v[220:223], v[4:7]
	v_mfma_f32_16x16x32_bf16 v[56:59], v[184:187], v[200:203], v[56:59]
	v_mfma_f32_16x16x32_bf16 v[48:51], v[192:195], v[200:203], v[48:51]
	v_mfma_f32_16x16x32_bf16 v[40:43], v[184:187], v[208:211], v[40:43]
	v_mfma_f32_16x16x32_bf16 v[32:35], v[192:195], v[208:211], v[32:35]
	v_mfma_f32_16x16x32_bf16 v[24:27], v[184:187], v[216:219], v[24:27]
	v_mfma_f32_16x16x32_bf16 v[16:19], v[192:195], v[216:219], v[16:19]
	v_mfma_f32_16x16x32_bf16 v[8:11], v[184:187], v[224:227], v[8:11]
	v_mfma_f32_16x16x32_bf16 v[4:7], v[192:195], v[224:227], v[4:7]
	s_setprio 0
	s_barrier
	s_add_i32 s35, s35, 2
	s_add_u32 s31, s31, 0x100
	s_addc_u32 s34, s34, 0
	s_add_u32 s44, s44, 0x100
	s_addc_u32 s45, s45, 0
	s_cmp_gt_u32 s35, 29
	s_cbranch_scc0 .LBB0_342
	s_and_b64 vcc, exec, s[22:23]
	s_cbranch_vccz .LBB0_345
	s_barrier

.Lgu_skip1:
	s_waitcnt lgkmcnt(0)
	s_barrier
	s_setprio 1
	s_waitcnt lgkmcnt(0)
	v_mfma_f32_16x16x32_bf16 v[124:127], v[142:145], v[184:187], v[124:127]
	v_mfma_f32_16x16x32_bf16 v[120:123], v[150:153], v[184:187], v[120:123]
	v_mfma_f32_16x16x32_bf16 v[112:115], v[142:145], v[192:195], v[112:115]
	v_mfma_f32_16x16x32_bf16 v[104:107], v[150:153], v[192:195], v[104:107]
	v_mfma_f32_16x16x32_bf16 v[96:99], v[142:145], v[200:203], v[96:99]
	v_mfma_f32_16x16x32_bf16 v[88:91], v[150:153], v[200:203], v[88:91]
	v_mfma_f32_16x16x32_bf16 v[80:83], v[142:145], v[208:211], v[80:83]
	v_mfma_f32_16x16x32_bf16 v[72:75], v[150:153], v[208:211], v[72:75]
	v_mfma_f32_16x16x32_bf16 v[124:127], v[146:149], v[188:191], v[124:127]
	v_mfma_f32_16x16x32_bf16 v[120:123], v[154:157], v[188:191], v[120:123]
	v_mfma_f32_16x16x32_bf16 v[112:115], v[146:149], v[196:199], v[112:115]
	v_mfma_f32_16x16x32_bf16 v[104:107], v[154:157], v[196:199], v[104:107]
	v_mfma_f32_16x16x32_bf16 v[96:99], v[146:149], v[204:207], v[96:99]
	v_mfma_f32_16x16x32_bf16 v[88:91], v[154:157], v[204:207], v[88:91]
	v_mfma_f32_16x16x32_bf16 v[80:83], v[146:149], v[212:215], v[80:83]
	v_mfma_f32_16x16x32_bf16 v[72:75], v[154:157], v[212:215], v[72:75]
	v_mfma_f32_16x16x32_bf16 v[128:131], v[168:171], v[184:187], v[128:131]
	v_mfma_f32_16x16x32_bf16 v[116:119], v[176:179], v[184:187], v[116:119]
	v_mfma_f32_16x16x32_bf16 v[108:111], v[168:171], v[192:195], v[108:111]
	v_mfma_f32_16x16x32_bf16 v[100:103], v[176:179], v[192:195], v[100:103]
	v_mfma_f32_16x16x32_bf16 v[92:95], v[168:171], v[200:203], v[92:95]
	v_mfma_f32_16x16x32_bf16 v[84:87], v[176:179], v[200:203], v[84:87]
	v_mfma_f32_16x16x32_bf16 v[76:79], v[168:171], v[208:211], v[76:79]
	v_mfma_f32_16x16x32_bf16 v[68:71], v[176:179], v[208:211], v[68:71]
	v_mfma_f32_16x16x32_bf16 v[128:131], v[172:175], v[188:191], v[128:131]
	v_mfma_f32_16x16x32_bf16 v[116:119], v[180:183], v[188:191], v[116:119]
	v_mfma_f32_16x16x32_bf16 v[108:111], v[172:175], v[196:199], v[108:111]
	v_mfma_f32_16x16x32_bf16 v[100:103], v[180:183], v[196:199], v[100:103]
	v_mfma_f32_16x16x32_bf16 v[92:95], v[172:175], v[204:207], v[92:95]
	v_mfma_f32_16x16x32_bf16 v[84:87], v[180:183], v[204:207], v[84:87]
	v_mfma_f32_16x16x32_bf16 v[76:79], v[172:175], v[212:215], v[76:79]
	v_mfma_f32_16x16x32_bf16 v[68:71], v[180:183], v[212:215], v[68:71]
	s_setprio 0
	s_barrier
	s_add_i32 s12, s14, s56
	s_mov_b32 m0, s12
	ds_read_b128 v[184:187], v167 offset:16384
	ds_read_b128 v[188:191], v167 offset:17408
	ds_read_b128 v[192:195], v167 offset:18432
	ds_read_b128 v[196:199], v167 offset:19456
	ds_read_b128 v[200:203], v167 offset:20480
	ds_read_b128 v[204:207], v167 offset:21504
	ds_read_b128 v[208:211], v167 offset:22528
	ds_read_b128 v[212:215], v167 offset:23552
	global_load_lds_dwordx4 v2, s[46:47]
	s_add_i32 m0, s12, 0x2000
	s_add_u32 s12, s46, 0x80000
	s_addc_u32 s13, s47, 0
	s_add_i32 s14, s15, s56
	global_load_lds_dwordx4 v0, s[46:47]
	s_mov_b32 m0, s14
	s_nop 0
	global_load_lds_dwordx4 v2, s[12:13]
	s_add_i32 m0, s14, 0x2000
	s_nop 0
	global_load_lds_dwordx4 v0, s[12:13]
	s_mov_b32 m0, s60
	s_nop 0
	global_load_lds_dwordx4 v134, s[48:49]
	s_mov_b32 m0, s61
	s_nop 0
	global_load_lds_dwordx4 v132, s[48:49]
	s_cmp_lg_u32 s32, 0
	s_cbranch_scc1 .Lgu_skip2
	s_waitcnt vmcnt(8)
.Lgu_skip2:
	s_mov_b32 s32, 0
	s_waitcnt lgkmcnt(0)
	s_barrier
	s_setprio 1
	s_waitcnt lgkmcnt(0)
	v_mfma_f32_16x16x32_bf16 v[64:67], v[142:145], v[184:187], v[64:67]
	v_mfma_f32_16x16x32_bf16 v[56:59], v[150:153], v[184:187], v[56:59]
	v_mfma_f32_16x16x32_bf16 v[48:51], v[142:145], v[192:195], v[48:51]
	v_mfma_f32_16x16x32_bf16 v[40:43], v[150:153], v[192:195], v[40:43]
	v_mfma_f32_16x16x32_bf16 v[32:35], v[142:145], v[200:203], v[32:35]
	v_mfma_f32_16x16x32_bf16 v[24:27], v[150:153], v[200:203], v[24:27]
	v_mfma_f32_16x16x32_bf16 v[16:19], v[142:145], v[208:211], v[16:19]
	v_mfma_f32_16x16x32_bf16 v[8:11], v[150:153], v[208:211], v[8:11]
	v_mfma_f32_16x16x32_bf16 v[64:67], v[146:149], v[188:191], v[64:67]
	v_mfma_f32_16x16x32_bf16 v[56:59], v[154:157], v[188:191], v[56:59]
	v_mfma_f32_16x16x32_bf16 v[48:51], v[146:149], v[196:199], v[48:51]
	v_mfma_f32_16x16x32_bf16 v[40:43], v[154:157], v[196:199], v[40:43]
	v_mfma_f32_16x16x32_bf16 v[32:35], v[146:149], v[204:207], v[32:35]
	v_mfma_f32_16x16x32_bf16 v[24:27], v[154:157], v[204:207], v[24:27]
	v_mfma_f32_16x16x32_bf16 v[16:19], v[146:149], v[212:215], v[16:19]
	v_mfma_f32_16x16x32_bf16 v[8:11], v[154:157], v[212:215], v[8:11]
	v_mfma_f32_16x16x32_bf16 v[60:63], v[168:171], v[184:187], v[60:63]
	v_mfma_f32_16x16x32_bf16 v[52:55], v[176:179], v[184:187], v[52:55]
	v_mfma_f32_16x16x32_bf16 v[44:47], v[168:171], v[192:195], v[44:47]
	v_mfma_f32_16x16x32_bf16 v[36:39], v[176:179], v[192:195], v[36:39]
	v_mfma_f32_16x16x32_bf16 v[28:31], v[168:171], v[200:203], v[28:31]
	v_mfma_f32_16x16x32_bf16 v[20:23], v[176:179], v[200:203], v[20:23]
	v_mfma_f32_16x16x32_bf16 v[12:15], v[168:171], v[208:211], v[12:15]
	v_mfma_f32_16x16x32_bf16 v[4:7], v[176:179], v[208:211], v[4:7]
	v_mfma_f32_16x16x32_bf16 v[60:63], v[172:175], v[188:191], v[60:63]
	v_mfma_f32_16x16x32_bf16 v[52:55], v[180:183], v[188:191], v[52:55]
	v_mfma_f32_16x16x32_bf16 v[44:47], v[172:175], v[196:199], v[44:47]
	v_mfma_f32_16x16x32_bf16 v[36:39], v[180:183], v[196:199], v[36:39]
	v_mfma_f32_16x16x32_bf16 v[28:31], v[172:175], v[204:207], v[28:31]
	v_mfma_f32_16x16x32_bf16 v[20:23], v[180:183], v[204:207], v[20:23]
	v_mfma_f32_16x16x32_bf16 v[12:15], v[172:175], v[212:215], v[12:15]
	v_mfma_f32_16x16x32_bf16 v[4:7], v[180:183], v[212:215], v[4:7]
	s_setprio 0
	s_barrier
	s_add_i32 s14, 0, 0x18000
	s_add_i32 s15, 0, 0x1c000
	v_add_u32_e32 v154, s14, v163
	v_add_u32_e32 v160, s15, v163
	ds_read_b128 v[142:145], v154
	ds_read_b128 v[146:149], v154 offset:1024
	ds_read_b128 v[150:153], v154 offset:2048
	ds_read_b128 v[154:157], v154 offset:3072
	ds_read_b128 v[168:171], v160
	ds_read_b128 v[172:175], v160 offset:1024
	ds_read_b128 v[176:179], v160 offset:2048
	ds_read_b128 v[180:183], v160 offset:3072
	s_add_u32 s12, s48, 0x80000
	s_addc_u32 s13, s49, 0
	s_mov_b32 m0, s62
	ds_read_b128 v[184:187], v167 offset:32768
	ds_read_b128 v[188:191], v167 offset:33792
	ds_read_b128 v[192:195], v167 offset:34816
	ds_read_b128 v[196:199], v167 offset:35840
	ds_read_b128 v[200:203], v167 offset:36864
	ds_read_b128 v[204:207], v167 offset:37888
	ds_read_b128 v[208:211], v167 offset:38912
	ds_read_b128 v[212:215], v167 offset:39936
	global_load_lds_dwordx4 v134, s[12:13]
	s_mov_b32 m0, s63
	s_nop 0
	global_load_lds_dwordx4 v132, s[12:13]
	s_waitcnt vmcnt(8)
	s_waitcnt lgkmcnt(0)
	s_barrier
	s_setprio 1
	s_waitcnt lgkmcnt(0)
	v_mfma_f32_16x16x32_bf16 v[124:127], v[142:145], v[184:187], v[124:127]
	v_mfma_f32_16x16x32_bf16 v[120:123], v[150:153], v[184:187], v[120:123]
	v_mfma_f32_16x16x32_bf16 v[112:115], v[142:145], v[192:195], v[112:115]
	v_mfma_f32_16x16x32_bf16 v[104:107], v[150:153], v[192:195], v[104:107]
	v_mfma_f32_16x16x32_bf16 v[96:99], v[142:145], v[200:203], v[96:99]
	v_mfma_f32_16x16x32_bf16 v[88:91], v[150:153], v[200:203], v[88:91]
	v_mfma_f32_16x16x32_bf16 v[80:83], v[142:145], v[208:211], v[80:83]
	v_mfma_f32_16x16x32_bf16 v[72:75], v[150:153], v[208:211], v[72:75]
	v_mfma_f32_16x16x32_bf16 v[124:127], v[146:149], v[188:191], v[124:127]
	v_mfma_f32_16x16x32_bf16 v[120:123], v[154:157], v[188:191], v[120:123]
	v_mfma_f32_16x16x32_bf16 v[112:115], v[146:149], v[196:199], v[112:115]
	v_mfma_f32_16x16x32_bf16 v[104:107], v[154:157], v[196:199], v[104:107]
	v_mfma_f32_16x16x32_bf16 v[96:99], v[146:149], v[204:207], v[96:99]
	v_mfma_f32_16x16x32_bf16 v[88:91], v[154:157], v[204:207], v[88:91]
	v_mfma_f32_16x16x32_bf16 v[80:83], v[146:149], v[212:215], v[80:83]
	v_mfma_f32_16x16x32_bf16 v[72:75], v[154:157], v[212:215], v[72:75]
	v_mfma_f32_16x16x32_bf16 v[128:131], v[168:171], v[184:187], v[128:131]
	v_mfma_f32_16x16x32_bf16 v[116:119], v[176:179], v[184:187], v[116:119]
	v_mfma_f32_16x16x32_bf16 v[108:111], v[168:171], v[192:195], v[108:111]
	v_mfma_f32_16x16x32_bf16 v[100:103], v[176:179], v[192:195], v[100:103]
	v_mfma_f32_16x16x32_bf16 v[92:95], v[168:171], v[200:203], v[92:95]
	v_mfma_f32_16x16x32_bf16 v[84:87], v[176:179], v[200:203], v[84:87]
	v_mfma_f32_16x16x32_bf16 v[76:79], v[168:171], v[208:211], v[76:79]
	v_mfma_f32_16x16x32_bf16 v[68:71], v[176:179], v[208:211], v[68:71]
	v_mfma_f32_16x16x32_bf16 v[128:131], v[172:175], v[188:191], v[128:131]
	v_mfma_f32_16x16x32_bf16 v[116:119], v[180:183], v[188:191], v[116:119]
	v_mfma_f32_16x16x32_bf16 v[108:111], v[172:175], v[196:199], v[108:111]
	v_mfma_f32_16x16x32_bf16 v[100:103], v[180:183], v[196:199], v[100:103]
	v_mfma_f32_16x16x32_bf16 v[92:95], v[172:175], v[204:207], v[92:95]
	v_mfma_f32_16x16x32_bf16 v[84:87], v[180:183], v[204:207], v[84:87]
	v_mfma_f32_16x16x32_bf16 v[76:79], v[172:175], v[212:215], v[76:79]
	v_mfma_f32_16x16x32_bf16 v[68:71], v[180:183], v[212:215], v[68:71]
	s_setprio 0
	s_barrier
	s_add_i32 s12, s14, s56
	s_mov_b32 m0, s12
	ds_read_b128 v[184:187], v167 offset:49152
	ds_read_b128 v[188:191], v167 offset:50176
	ds_read_b128 v[192:195], v167 offset:51200
	ds_read_b128 v[196:199], v167 offset:52224
	ds_read_b128 v[200:203], v167 offset:53248
	ds_read_b128 v[204:207], v167 offset:54272
	ds_read_b128 v[208:211], v167 offset:55296
	ds_read_b128 v[212:215], v167 offset:56320
	s_add_u32 s100, s46, 0x80
	s_addc_u32 s101, s47, 0
	global_load_lds_dwordx4 v2, s[100:101]
	s_add_i32 m0, s12, 0x2000
	s_add_u32 s12, s46, 0x80080
	s_addc_u32 s13, s47, 0
	s_add_i32 s14, s15, s56
	s_add_u32 s100, s46, 0x80
	s_addc_u32 s101, s47, 0
	global_load_lds_dwordx4 v0, s[100:101]
	s_mov_b32 m0, s14
	s_nop 0
	global_load_lds_dwordx4 v2, s[12:13]
	s_add_i32 m0, s14, 0x2000
	s_nop 0
	global_load_lds_dwordx4 v0, s[12:13]
	s_mov_b32 m0, s64
	s_nop 0
	s_add_u32 s100, s48, 0x80
	s_addc_u32 s101, s49, 0
	global_load_lds_dwordx4 v134, s[100:101]
	s_mov_b32 m0, s65
	s_nop 0
	s_add_u32 s100, s48, 0x80
	s_addc_u32 s101, s49, 0
	global_load_lds_dwordx4 v132, s[100:101]
	s_waitcnt vmcnt(8)
	s_waitcnt lgkmcnt(0)
	s_barrier
	s_setprio 1
	s_waitcnt lgkmcnt(0)
	v_mfma_f32_16x16x32_bf16 v[64:67], v[142:145], v[184:187], v[64:67]
	v_mfma_f32_16x16x32_bf16 v[56:59], v[150:153], v[184:187], v[56:59]
	v_mfma_f32_16x16x32_bf16 v[48:51], v[142:145], v[192:195], v[48:51]
	v_mfma_f32_16x16x32_bf16 v[40:43], v[150:153], v[192:195], v[40:43]
	v_mfma_f32_16x16x32_bf16 v[32:35], v[142:145], v[200:203], v[32:35]
	v_mfma_f32_16x16x32_bf16 v[24:27], v[150:153], v[200:203], v[24:27]
	v_mfma_f32_16x16x32_bf16 v[16:19], v[142:145], v[208:211], v[16:19]
	v_mfma_f32_16x16x32_bf16 v[8:11], v[150:153], v[208:211], v[8:11]
	v_mfma_f32_16x16x32_bf16 v[64:67], v[146:149], v[188:191], v[64:67]
	v_mfma_f32_16x16x32_bf16 v[56:59], v[154:157], v[188:191], v[56:59]
	v_mfma_f32_16x16x32_bf16 v[48:51], v[146:149], v[196:199], v[48:51]
	v_mfma_f32_16x16x32_bf16 v[40:43], v[154:157], v[196:199], v[40:43]
	v_mfma_f32_16x16x32_bf16 v[32:35], v[146:149], v[204:207], v[32:35]
	v_mfma_f32_16x16x32_bf16 v[24:27], v[154:157], v[204:207], v[24:27]
	v_mfma_f32_16x16x32_bf16 v[16:19], v[146:149], v[212:215], v[16:19]
	v_mfma_f32_16x16x32_bf16 v[8:11], v[154:157], v[212:215], v[8:11]
	v_mfma_f32_16x16x32_bf16 v[60:63], v[168:171], v[184:187], v[60:63]
	v_mfma_f32_16x16x32_bf16 v[52:55], v[176:179], v[184:187], v[52:55]
	v_mfma_f32_16x16x32_bf16 v[44:47], v[168:171], v[192:195], v[44:47]
	v_mfma_f32_16x16x32_bf16 v[36:39], v[176:179], v[192:195], v[36:39]
	v_mfma_f32_16x16x32_bf16 v[28:31], v[168:171], v[200:203], v[28:31]
	v_mfma_f32_16x16x32_bf16 v[20:23], v[176:179], v[200:203], v[20:23]
	v_mfma_f32_16x16x32_bf16 v[12:15], v[168:171], v[208:211], v[12:15]
	v_mfma_f32_16x16x32_bf16 v[4:7], v[176:179], v[208:211], v[4:7]
	v_mfma_f32_16x16x32_bf16 v[60:63], v[172:175], v[188:191], v[60:63]
	v_mfma_f32_16x16x32_bf16 v[52:55], v[180:183], v[188:191], v[52:55]
	v_mfma_f32_16x16x32_bf16 v[44:47], v[172:175], v[196:199], v[44:47]
	v_mfma_f32_16x16x32_bf16 v[36:39], v[180:183], v[196:199], v[36:39]
	v_mfma_f32_16x16x32_bf16 v[28:31], v[172:175], v[204:207], v[28:31]
	v_mfma_f32_16x16x32_bf16 v[20:23], v[180:183], v[204:207], v[20:23]
	v_mfma_f32_16x16x32_bf16 v[12:15], v[172:175], v[212:215], v[12:15]
	v_mfma_f32_16x16x32_bf16 v[4:7], v[180:183], v[212:215], v[4:7]
	s_setprio 0
	s_barrier
	s_add_i32 s11, s11, 2
	s_add_u32 s9, s9, 0x100
	s_addc_u32 s10, s10, 0
	s_add_u32 s44, s44, 0x100
	s_addc_u32 s45, s45, 0
	s_cmp_gt_u32 s11, 29
	s_cbranch_scc0 .LBB0_1066
	s_and_b64 vcc, exec, s[22:23]
	s_cbranch_vccz .LBB0_1069
	s_barrier
